# combined v35 + attention unit top no longer drains the previous unit's stores before its barrier
# baseline (speedup 1.0000x reference)
.LBB0_790:
	s_barrier
	v_readfirstlane_b32 s100, v235
	s_nop 3
	s_mul_i32 s101, s100, s42
	s_sub_i32 s0, s42, 1
	s_sub_i32 s0, s0, s2
	s_bitcmp0_b32 s100, 0
	s_cselect_b32 s0, s2, s0
	s_add_i32 s101, s101, s0
	v_add_u32_e32 v235, 1, v235
	v_mov_b32_e32 v0, s101
	s_movk_i32 s0, 0x480
	s_mov_b64 s[8:9], -1
	v_cmp_gt_i32_e64 s[6:7], s0, v0
	s_and_saveexec_b64 s[68:69], s[6:7]
	s_cbranch_execz .LBB0_789
	v_ashrrev_i32_e32 v1, 31, v0
	v_lshrrev_b32_e32 v1, 25, v1
	v_add_u32_e32 v1, v0, v1
	v_ashrrev_i32_e32 v8, 7, v1
	v_and_b32_e32 v1, 0xffffff80, v1
	v_sub_u32_e32 v0, v0, v1
	v_mov_b32_e32 v1, 11
	v_lshrrev_b16_sdwa v1, v1, sext(v0) dst_sel:DWORD dst_unused:UNUSED_PAD src0_sel:DWORD src1_sel:BYTE_0
	v_and_b32_e32 v1, 15, v1
	v_add_u16_e32 v1, v0, v1
	v_sub_u32_e32 v9, 8, v8
	v_ashrrev_i16_sdwa v2, v198, sext(v1) dst_sel:DWORD dst_unused:UNUSED_PAD src0_sel:DWORD src1_sel:BYTE_0
	s_movk_i32 s0, 0x810
	v_and_b32_e32 v1, 0xf0, v1
	v_mul_hi_i32_i24_sdwa v135, sext(v2), s0 dst_sel:DWORD dst_unused:UNUSED_PAD src0_sel:WORD_0 src1_sel:DWORD
	v_mul_i32_i24_sdwa v134, sext(v2), s0 dst_sel:DWORD dst_unused:UNUSED_PAD src0_sel:WORD_0 src1_sel:DWORD
	v_mul_hi_i32_i24_e32 v3, 0x2040, v0
	v_mul_i32_i24_e32 v2, 0x2040, v0
	v_lshlrev_b32_e32 v10, 8, v9
	v_sub_u16_e32 v4, v0, v1
	v_lshl_add_u64 v[140:141], s[62:63], 0, v[2:3]
	v_add_u32_e32 v164, v10, v156
	v_mov_b32_e32 v2, 6
	v_lshlrev_b32_sdwa v138, v2, sext(v4) dst_sel:DWORD dst_unused:UNUSED_PAD src0_sel:DWORD src1_sel:BYTE_0
	v_max_i32_e32 v6, 0xf0, v164
	v_ashrrev_i32_e32 v139, 31, v138
	v_add_u32_e32 v172, 0xffffff10, v6
	v_lshlrev_b64 v[2:3], 1, v[138:139]
	v_lshl_add_u64 v[6:7], v[134:135], 0, v[172:173]
	v_lshl_add_u64 v[4:5], v[120:121], 0, v[2:3]
	v_lshlrev_b64 v[6:7], 12, v[6:7]
	v_lshl_add_u64 v[6:7], v[4:5], 0, v[6:7]
	v_or_b32_e32 v139, 16, v164
	global_load_dwordx4 v[20:23], v[6:7], off
	global_load_dwordx4 v[24:27], v[6:7], off offset:64
	v_max_i32_e32 v6, 0xf0, v139
	v_add_u32_e32 v172, 0xffffff10, v6
	v_lshl_add_u64 v[6:7], v[134:135], 0, v[172:173]
	v_lshlrev_b64 v[6:7], 12, v[6:7]
	v_ashrrev_i32_e32 v1, 31, v0
	v_lshl_add_u64 v[4:5], v[4:5], 0, v[6:7]
	global_load_dwordx4 v[28:31], v[4:5], off
	global_load_dwordx4 v[32:35], v[4:5], off offset:64
	v_lshl_add_u64 v[4:5], v[134:135], 0, v[124:125]
	v_lshlrev_b64 v[0:1], 6, v[0:1]
	v_lshlrev_b64 v[4:5], 11, v[4:5]
	v_lshl_add_u64 v[0:1], v[0:1], 0, v[122:123]
	v_mov_b64_e32 v[6:7], s[88:89]
	v_lshl_add_u64 v[4:5], s[70:71], 0, v[4:5]
	v_mad_u64_u32 v[144:145], s[6:7], v0, s52, v[6:7]
	v_lshl_add_u64 v[4:5], v[4:5], 0, v[2:3]
	v_lshlrev_b32_e32 v142, 1, v126
	v_mov_b32_e32 v143, v173
	v_mad_i32_i24 v145, v1, s52, v145
	v_mov_b32_e32 v131, v173
	v_lshlrev_b32_e32 v165, 2, v9
	v_lshl_add_u64 v[4:5], v[4:5], 0, v[142:143]
	v_lshl_add_u64 v[0:1], v[144:145], 0, v[130:131]
	v_mov_b32_e32 v133, v173
	v_or_b32_e32 v166, 3, v165
	global_load_dwordx4 v[36:39], v[4:5], off
	global_load_dwordx4 v[40:43], v[0:1], off offset:-96
	v_lshl_add_u64 v[0:1], v[140:141], 0, v[132:133]
	global_load_dword v131, v[0:1], off offset:-192
	v_min_u32_e32 v0, 4, v166
	v_lshl_add_u32 v6, v0, 6, v201
	v_add_u32_e32 v0, v6, v122
	v_max_i32_e32 v172, 0, v0
	v_lshl_add_u64 v[0:1], v[134:135], 0, v[172:173]
	v_lshlrev_b64 v[0:1], 11, v[0:1]
	v_lshl_add_u64 v[0:1], s[70:71], 0, v[0:1]
	v_add_u32_e32 v4, v6, v126
	v_lshl_add_u64 v[0:1], v[0:1], 0, v[2:3]
	v_max_i32_e32 v4, 0, v4
	v_lshl_add_u64 v[0:1], v[0:1], 0, v[142:143]
	v_lshlrev_b32_e32 v172, 1, v4
	v_lshl_add_u64 v[4:5], v[144:145], 0, v[172:173]
	global_load_dwordx4 v[44:47], v[0:1], off
	global_load_dwordx4 v[48:51], v[4:5], off
	v_add_u32_e32 v0, v6, v154
	v_max_i32_e32 v0, 0, v0
	v_lshlrev_b32_e32 v172, 2, v0
	v_lshl_add_u64 v[0:1], v[140:141], 0, v[172:173]
	global_load_dword v167, v[0:1], off
	v_min_u32_e32 v0, 5, v166
	v_lshl_add_u32 v6, v0, 6, v201
	v_add_u32_e32 v0, v6, v122
	v_max_i32_e32 v172, 0, v0
	v_lshl_add_u64 v[0:1], v[134:135], 0, v[172:173]
	v_lshlrev_b64 v[0:1], 11, v[0:1]
	v_lshl_add_u64 v[0:1], s[70:71], 0, v[0:1]
	v_add_u32_e32 v4, v6, v126
	v_lshl_add_u64 v[0:1], v[0:1], 0, v[2:3]
	v_max_i32_e32 v4, 0, v4
	v_lshl_add_u64 v[0:1], v[0:1], 0, v[142:143]
	v_lshlrev_b32_e32 v172, 1, v4
	v_lshl_add_u64 v[4:5], v[144:145], 0, v[172:173]
	global_load_dwordx4 v[52:55], v[0:1], off
	global_load_dwordx4 v[56:59], v[4:5], off
	v_add_u32_e32 v0, v6, v154
	v_max_i32_e32 v0, 0, v0
	v_lshlrev_b32_e32 v172, 2, v0
	v_lshl_add_u64 v[0:1], v[140:141], 0, v[172:173]
	global_load_dword v169, v[0:1], off
	v_sub_u32_e32 v0, 0, v8
	v_or_b32_e32 v1, v10, v155
	v_lshl_add_u64 v[146:147], v[128:129], 0, v[2:3]
	v_lshlrev_b32_e32 v0, 8, v0
	v_mov_b32_e32 v2, v173
	v_mov_b32_e32 v3, v173
	v_add_u32_e32 v133, s85, v1
	v_sub_u32_e32 v168, 0, v0
	v_mov_b32_e32 v172, v173
	v_mov_b32_e32 v0, v173
	v_mov_b32_e32 v1, v173
	v_mov_b64_e32 v[6:7], v[2:3]
	v_mov_b64_e32 v[10:11], v[2:3]
	v_mov_b64_e32 v[14:15], v[2:3]
	v_mov_b64_e32 v[18:19], v[2:3]
	v_mov_b64_e32 v[62:63], v[2:3]
	v_mov_b64_e32 v[66:67], v[2:3]
	v_mov_b64_e32 v[70:71], v[2:3]
	s_mov_b32 s60, s87
	s_mov_b32 s84, 0
	v_or_b32_e32 v143, 16, v133
	v_mov_b32_e32 v148, 0xff800000
	s_mov_b64 s[34:35], 0
	v_mov_b32_e32 v170, 0
	s_mov_b32 s87, 0
	v_mov_b64_e32 v[4:5], v[0:1]
	v_mov_b64_e32 v[8:9], v[0:1]
	v_mov_b64_e32 v[12:13], v[0:1]
	v_mov_b64_e32 v[16:17], v[0:1]
	v_mov_b64_e32 v[60:61], v[0:1]
	v_mov_b64_e32 v[64:65], v[0:1]
	v_mov_b64_e32 v[68:69], v[0:1]
	v_mov_b64_e32 v[136:137], v[172:173]
	v_mov_b32_e32 v149, 0xff800000
	v_min_u32_e32 v228, 6, v166
	v_lshl_add_u32 v234, v228, 6, v201
	v_add_u32_e32 v228, v234, v122
	v_add_u32_e32 v230, v234, v126
	v_max_i32_e32 v172, 0, v228
	v_max_i32_e32 v230, 0, v230
	v_lshl_add_u64 v[228:229], v[134:135], 0, v[172:173]
	v_lshlrev_b32_e32 v172, 1, v230
	v_add_u32_e32 v234, v234, v154
	v_lshlrev_b64 v[228:229], 11, v[228:229]
	v_lshl_add_u64 v[230:231], v[144:145], 0, v[172:173]
	v_max_i32_e32 v172, 0, v234
	v_lshl_add_u64 v[228:229], v[146:147], 0, v[228:229]
	v_lshl_add_u64 v[232:233], v[172:173], 2, v[140:141]
	v_mov_b32_e32 v172, v173
	s_branch .LBB0_798
